# PH8 epilogue output stores write-through (sc1) so the phase-end L2 write-back finds little dirty data
# speedup vs baseline: 1.0014x; 1.0005x over previous
; #define SBAR() __builtin_amdgcn_sched_barrier(0)
; __device__ __forceinline__ float fast_sigmoid(float x) { return __builtin_amdgcn_rcpf(1.0f + __builtin_amdgcn_exp2f(-1.4426950408889634f * x)); }
; __device__ __forceinline__ u32x4 pack8(const f32x4 a, const f32x4 b) { u32x4 w; w.x = cvt_pk_bf16(a[0], a[1]); w.y = cvt_pk_bf16(a[2], a[3]); w.z = cvt_pk_bf16(b[0], b[1]); w.w = cvt_pk_bf16(b[2], b[3]); return w; }
;     __device__ __forceinline__ void operator()(f32x4 (&acc)[2][2][4][2], const Unit& u, int wr, int wc, int fr, int fq) const {
;     ...
;         } else if constexpr (PH == 8) {
;             float rsv[8];
; #pragma unroll
;             for (int i = 0; i < 8; ++i) rsv[i] = P.ssq_h1_()[ROWOF(i >> 2, i & 3)];
;             SBAR();
; #pragma unroll
;             for (int ai = 0; ai < 2; ++ai)
; #pragma unroll
;                 for (int m = 0; m < 4; ++m) { const int row = ROWOF(ai, m); const float rs = rsqrtf(rsv[ai * 4 + m] * (1.0f / 2048.0f) + EPS);
;                     f32x4 g0 = acc[ai][0][m][0] * rs, g1 = acc[ai][0][m][1] * rs; const f32x4 u0 = acc[ai][1][m][0] * rs, u1 = acc[ai][1][m][1] * rs;
; #pragma unroll
;                     for (int j = 0; j < 4; ++j) { g0[j] = g0[j] * fast_sigmoid(g0[j]) * u0[j]; g1[j] = g1[j] * fast_sigmoid(g1[j]) * u1[j]; }
;                     *(u32x4*)(P.f_() + (size_t)row * DFF + u.pn * 128 + c8) = pack8(g0, g1); }
.LBB0_1002:
	v_lshl_add_u32 v146, s22, 8, v150
	v_ashrrev_i32_e32 v147, 31, v146
	v_lshl_add_u64 v[156:157], v[146:147], 2, s[10:11]
	global_load_dword v158, v[156:157], off
	global_load_dword v159, v[156:157], off offset:64
	global_load_dword v164, v[156:157], off offset:128
	global_load_dword v165, v[156:157], off offset:192
	global_load_dword v166, v[156:157], off offset:512
	global_load_dword v149, v[156:157], off offset:576
	global_load_dword v148, v[156:157], off offset:640
	global_load_dword v147, v[156:157], off offset:704
	v_add_u32_e32 v156, 0x80, v146
	s_waitcnt vmcnt(0)
	s_lshl_b32 s22, s23, 7
	s_ashr_i32 s23, s22, 31
	s_lshl_b64 s[22:23], s[22:23], 1
	s_add_u32 s98, s12, s22
	s_addc_u32 s99, s13, s23
	s_mov_b32 s36, 0xbfb8aa3b
	s_mov_b32 s37, 0xbfb8aa3b
	s_mov_b32 s38, 1.0
	s_mov_b32 s39, 1.0
	v_fmamk_f32 v228, v158, 0x3a000000, v155
	v_mul_f32_e32 v229, 0x4b800000, v228
	v_cmp_gt_f32_e32 vcc, s51, v228
	s_nop 1
	v_cndmask_b32_e32 v228, v228, v229, vcc
	v_mad_u32_u24 v157, v146, s52, v134
	v_rsq_f32_e32 v228, v228
	s_nop 0
	v_mul_f32_e32 v229, 0x45800000, v228
	s_nop 0
	v_cndmask_b32_e32 v228, v228, v229, vcc
	v_pk_mul_f32 v[126:127], v[126:127], v[228:229] op_sel_hi:[1,0]
	v_pk_mul_f32 v[128:129], v[128:129], v[228:229] op_sel_hi:[1,0]
	v_pk_mul_f32 v[122:123], v[122:123], v[228:229] op_sel_hi:[1,0]
	v_pk_mul_f32 v[124:125], v[124:125], v[228:229] op_sel_hi:[1,0]
	v_pk_mul_f32 v[118:119], v[118:119], v[228:229] op_sel_hi:[1,0]
	v_pk_mul_f32 v[120:121], v[120:121], v[228:229] op_sel_hi:[1,0]
	v_pk_mul_f32 v[114:115], v[114:115], v[228:229] op_sel_hi:[1,0]
	v_pk_mul_f32 v[116:117], v[116:117], v[228:229] op_sel_hi:[1,0]
	v_pk_mul_f32 v[220:221], v[126:127], s[36:37]
	v_pk_mul_f32 v[222:223], v[128:129], s[36:37]
	v_pk_mul_f32 v[224:225], v[122:123], s[36:37]
	v_pk_mul_f32 v[226:227], v[124:125], s[36:37]
	v_exp_f32_e32 v220, v220
	v_exp_f32_e32 v221, v221
	v_exp_f32_e32 v222, v222
	v_exp_f32_e32 v223, v223
	v_exp_f32_e32 v224, v224
	v_exp_f32_e32 v225, v225
	v_exp_f32_e32 v226, v226
	v_exp_f32_e32 v227, v227
	v_pk_add_f32 v[220:221], v[220:221], s[38:39]
	v_pk_add_f32 v[222:223], v[222:223], s[38:39]
	v_pk_add_f32 v[224:225], v[224:225], s[38:39]
	v_pk_add_f32 v[226:227], v[226:227], s[38:39]
	v_rcp_f32_e32 v220, v220
	v_rcp_f32_e32 v221, v221
	v_rcp_f32_e32 v222, v222
	v_rcp_f32_e32 v223, v223
	v_rcp_f32_e32 v224, v224
	v_rcp_f32_e32 v225, v225
	v_rcp_f32_e32 v226, v226
	v_rcp_f32_e32 v227, v227
	v_pk_mul_f32 v[126:127], v[126:127], v[220:221]
	v_pk_mul_f32 v[128:129], v[128:129], v[222:223]
	v_pk_mul_f32 v[122:123], v[122:123], v[224:225]
	v_pk_mul_f32 v[124:125], v[124:125], v[226:227]
	v_pk_mul_f32 v[118:119], v[118:119], v[126:127]
	v_pk_mul_f32 v[120:121], v[120:121], v[128:129]
	v_pk_mul_f32 v[114:115], v[114:115], v[122:123]
	v_pk_mul_f32 v[116:117], v[116:117], v[124:125]
	v_cvt_pk_bf16_f32 v126, v118, v119
	v_cvt_pk_bf16_f32 v127, v120, v121
	v_cvt_pk_bf16_f32 v128, v114, v115
	v_cvt_pk_bf16_f32 v129, v116, v117
	global_store_dwordx4 v157, v[126:129], s[98:99] sc1
	v_fmamk_f32 v228, v159, 0x3a000000, v155
	v_mul_f32_e32 v229, 0x4b800000, v228
	v_cmp_gt_f32_e32 vcc, s51, v228
	v_or_b32_e32 v156, 0x10, v146
	s_nop 0
	v_cndmask_b32_e32 v228, v228, v229, vcc
	v_mad_u32_u24 v160, v156, s52, v134
	v_rsq_f32_e32 v228, v228
	s_nop 0
	v_mul_f32_e32 v229, 0x45800000, v228
	s_nop 0
	v_cndmask_b32_e32 v228, v228, v229, vcc
	v_pk_mul_f32 v[110:111], v[110:111], v[228:229] op_sel_hi:[1,0]
	v_pk_mul_f32 v[112:113], v[112:113], v[228:229] op_sel_hi:[1,0]
	v_pk_mul_f32 v[106:107], v[106:107], v[228:229] op_sel_hi:[1,0]
	v_pk_mul_f32 v[108:109], v[108:109], v[228:229] op_sel_hi:[1,0]
	v_pk_mul_f32 v[102:103], v[102:103], v[228:229] op_sel_hi:[1,0]
	v_pk_mul_f32 v[104:105], v[104:105], v[228:229] op_sel_hi:[1,0]
	v_pk_mul_f32 v[98:99], v[98:99], v[228:229] op_sel_hi:[1,0]
	v_pk_mul_f32 v[100:101], v[100:101], v[228:229] op_sel_hi:[1,0]
	v_pk_mul_f32 v[220:221], v[110:111], s[36:37]
	v_pk_mul_f32 v[222:223], v[112:113], s[36:37]
	v_pk_mul_f32 v[224:225], v[106:107], s[36:37]
	v_pk_mul_f32 v[226:227], v[108:109], s[36:37]
	v_exp_f32_e32 v220, v220
	v_exp_f32_e32 v221, v221
	v_exp_f32_e32 v222, v222
	v_exp_f32_e32 v223, v223
	v_exp_f32_e32 v224, v224
	v_exp_f32_e32 v225, v225
	v_exp_f32_e32 v226, v226
	v_exp_f32_e32 v227, v227
	v_pk_add_f32 v[220:221], v[220:221], s[38:39]
	v_pk_add_f32 v[222:223], v[222:223], s[38:39]
	v_pk_add_f32 v[224:225], v[224:225], s[38:39]
	v_pk_add_f32 v[226:227], v[226:227], s[38:39]
	v_rcp_f32_e32 v220, v220
	v_rcp_f32_e32 v221, v221
	v_rcp_f32_e32 v222, v222
	v_rcp_f32_e32 v223, v223
	v_rcp_f32_e32 v224, v224
	v_rcp_f32_e32 v225, v225
	v_rcp_f32_e32 v226, v226
	v_rcp_f32_e32 v227, v227
	v_pk_mul_f32 v[110:111], v[110:111], v[220:221]
	v_pk_mul_f32 v[112:113], v[112:113], v[222:223]
	v_pk_mul_f32 v[106:107], v[106:107], v[224:225]
	v_pk_mul_f32 v[108:109], v[108:109], v[226:227]
	v_pk_mul_f32 v[102:103], v[102:103], v[110:111]
	v_pk_mul_f32 v[104:105], v[104:105], v[112:113]
	v_pk_mul_f32 v[98:99], v[98:99], v[106:107]
	v_pk_mul_f32 v[100:101], v[100:101], v[108:109]
	v_cvt_pk_bf16_f32 v110, v102, v103
	v_cvt_pk_bf16_f32 v111, v104, v105
	v_cvt_pk_bf16_f32 v112, v98, v99
	v_cvt_pk_bf16_f32 v113, v100, v101
	global_store_dwordx4 v160, v[110:113], s[98:99] sc1
	v_fmamk_f32 v228, v164, 0x3a000000, v155
	v_mul_f32_e32 v229, 0x4b800000, v228
	v_cmp_gt_f32_e32 vcc, s51, v228
	v_or_b32_e32 v156, 0x20, v146
	s_nop 0
	v_cndmask_b32_e32 v228, v228, v229, vcc
	v_mad_u32_u24 v157, v156, s52, v134
	v_rsq_f32_e32 v228, v228
	s_nop 0
	v_mul_f32_e32 v229, 0x45800000, v228
	s_nop 0
	v_cndmask_b32_e32 v228, v228, v229, vcc
; __device__ __forceinline__ float fast_sigmoid(float x) { return __builtin_amdgcn_rcpf(1.0f + __builtin_amdgcn_exp2f(-1.4426950408889634f * x)); }
; __device__ __forceinline__ u32x4 pack8(const f32x4 a, const f32x4 b) { u32x4 w; w.x = cvt_pk_bf16(a[0], a[1]); w.y = cvt_pk_bf16(a[2], a[3]); w.z = cvt_pk_bf16(b[0], b[1]); w.w = cvt_pk_bf16(b[2], b[3]); return w; }
;     __device__ __forceinline__ void operator()(f32x4 (&acc)[2][2][4][2], const Unit& u, int wr, int wc, int fr, int fq) const {
;     ...
;             for (int ai = 0; ai < 2; ++ai)
; #pragma unroll
;                 for (int m = 0; m < 4; ++m) { const int row = ROWOF(ai, m); const float rs = rsqrtf(rsv[ai * 4 + m] * (1.0f / 2048.0f) + EPS);
;                     f32x4 g0 = acc[ai][0][m][0] * rs, g1 = acc[ai][0][m][1] * rs; const f32x4 u0 = acc[ai][1][m][0] * rs, u1 = acc[ai][1][m][1] * rs;
; #pragma unroll
;                     for (int j = 0; j < 4; ++j) { g0[j] = g0[j] * fast_sigmoid(g0[j]) * u0[j]; g1[j] = g1[j] * fast_sigmoid(g1[j]) * u1[j]; }
;                     *(u32x4*)(P.f_() + (size_t)row * DFF + u.pn * 128 + c8) = pack8(g0, g1); }
	v_pk_mul_f32 v[94:95], v[94:95], v[228:229] op_sel_hi:[1,0]
	v_pk_mul_f32 v[96:97], v[96:97], v[228:229] op_sel_hi:[1,0]
	v_pk_mul_f32 v[90:91], v[90:91], v[228:229] op_sel_hi:[1,0]
	v_pk_mul_f32 v[92:93], v[92:93], v[228:229] op_sel_hi:[1,0]
	v_pk_mul_f32 v[86:87], v[86:87], v[228:229] op_sel_hi:[1,0]
	v_pk_mul_f32 v[88:89], v[88:89], v[228:229] op_sel_hi:[1,0]
	v_pk_mul_f32 v[82:83], v[82:83], v[228:229] op_sel_hi:[1,0]
	v_pk_mul_f32 v[84:85], v[84:85], v[228:229] op_sel_hi:[1,0]
	v_pk_mul_f32 v[220:221], v[94:95], s[36:37]
	v_pk_mul_f32 v[222:223], v[96:97], s[36:37]
	v_pk_mul_f32 v[224:225], v[90:91], s[36:37]
	v_pk_mul_f32 v[226:227], v[92:93], s[36:37]
	v_exp_f32_e32 v220, v220
	v_exp_f32_e32 v221, v221
	v_exp_f32_e32 v222, v222
	v_exp_f32_e32 v223, v223
	v_exp_f32_e32 v224, v224
	v_exp_f32_e32 v225, v225
	v_exp_f32_e32 v226, v226
	v_exp_f32_e32 v227, v227
	v_pk_add_f32 v[220:221], v[220:221], s[38:39]
	v_pk_add_f32 v[222:223], v[222:223], s[38:39]
	v_pk_add_f32 v[224:225], v[224:225], s[38:39]
	v_pk_add_f32 v[226:227], v[226:227], s[38:39]
	v_rcp_f32_e32 v220, v220
	v_rcp_f32_e32 v221, v221
	v_rcp_f32_e32 v222, v222
	v_rcp_f32_e32 v223, v223
	v_rcp_f32_e32 v224, v224
	v_rcp_f32_e32 v225, v225
	v_rcp_f32_e32 v226, v226
	v_rcp_f32_e32 v227, v227
	v_pk_mul_f32 v[94:95], v[94:95], v[220:221]
	v_pk_mul_f32 v[96:97], v[96:97], v[222:223]
	v_pk_mul_f32 v[90:91], v[90:91], v[224:225]
	v_pk_mul_f32 v[92:93], v[92:93], v[226:227]
	v_pk_mul_f32 v[86:87], v[86:87], v[94:95]
	v_pk_mul_f32 v[88:89], v[88:89], v[96:97]
	v_pk_mul_f32 v[82:83], v[82:83], v[90:91]
	v_pk_mul_f32 v[84:85], v[84:85], v[92:93]
	v_cvt_pk_bf16_f32 v94, v86, v87
	v_cvt_pk_bf16_f32 v95, v88, v89
	v_cvt_pk_bf16_f32 v96, v82, v83
	v_cvt_pk_bf16_f32 v97, v84, v85
	global_store_dwordx4 v157, v[94:97], s[98:99] sc1
	v_fmamk_f32 v228, v165, 0x3a000000, v155
	v_mul_f32_e32 v229, 0x4b800000, v228
	v_cmp_gt_f32_e32 vcc, s51, v228
	v_or_b32_e32 v156, 0x30, v146
	s_nop 0
	v_cndmask_b32_e32 v228, v228, v229, vcc
	v_mad_u32_u24 v160, v156, s52, v134
	v_rsq_f32_e32 v228, v228
	s_nop 0
	v_mul_f32_e32 v229, 0x45800000, v228
	s_nop 0
	v_cndmask_b32_e32 v228, v228, v229, vcc
	v_pk_mul_f32 v[78:79], v[78:79], v[228:229] op_sel_hi:[1,0]
	v_pk_mul_f32 v[80:81], v[80:81], v[228:229] op_sel_hi:[1,0]
	v_pk_mul_f32 v[74:75], v[74:75], v[228:229] op_sel_hi:[1,0]
	v_pk_mul_f32 v[76:77], v[76:77], v[228:229] op_sel_hi:[1,0]
	v_pk_mul_f32 v[70:71], v[70:71], v[228:229] op_sel_hi:[1,0]
	v_pk_mul_f32 v[72:73], v[72:73], v[228:229] op_sel_hi:[1,0]
	v_pk_mul_f32 v[66:67], v[66:67], v[228:229] op_sel_hi:[1,0]
	v_pk_mul_f32 v[68:69], v[68:69], v[228:229] op_sel_hi:[1,0]
	v_pk_mul_f32 v[220:221], v[78:79], s[36:37]
	v_pk_mul_f32 v[222:223], v[80:81], s[36:37]
	v_pk_mul_f32 v[224:225], v[74:75], s[36:37]
	v_pk_mul_f32 v[226:227], v[76:77], s[36:37]
	v_exp_f32_e32 v220, v220
	v_exp_f32_e32 v221, v221
	v_exp_f32_e32 v222, v222
	v_exp_f32_e32 v223, v223
	v_exp_f32_e32 v224, v224
	v_exp_f32_e32 v225, v225
	v_exp_f32_e32 v226, v226
	v_exp_f32_e32 v227, v227
	v_pk_add_f32 v[220:221], v[220:221], s[38:39]
	v_pk_add_f32 v[222:223], v[222:223], s[38:39]
	v_pk_add_f32 v[224:225], v[224:225], s[38:39]
	v_pk_add_f32 v[226:227], v[226:227], s[38:39]
	v_rcp_f32_e32 v220, v220
	v_rcp_f32_e32 v221, v221
	v_rcp_f32_e32 v222, v222
	v_rcp_f32_e32 v223, v223
	v_rcp_f32_e32 v224, v224
	v_rcp_f32_e32 v225, v225
	v_rcp_f32_e32 v226, v226
	v_rcp_f32_e32 v227, v227
	v_pk_mul_f32 v[78:79], v[78:79], v[220:221]
	v_pk_mul_f32 v[80:81], v[80:81], v[222:223]
	v_pk_mul_f32 v[74:75], v[74:75], v[224:225]
	v_pk_mul_f32 v[76:77], v[76:77], v[226:227]
	v_pk_mul_f32 v[70:71], v[70:71], v[78:79]
	v_pk_mul_f32 v[72:73], v[72:73], v[80:81]
	v_pk_mul_f32 v[66:67], v[66:67], v[74:75]
	v_pk_mul_f32 v[68:69], v[68:69], v[76:77]
	v_cvt_pk_bf16_f32 v78, v70, v71
	v_cvt_pk_bf16_f32 v79, v72, v73
	v_cvt_pk_bf16_f32 v80, v66, v67
	v_cvt_pk_bf16_f32 v81, v68, v69
	global_store_dwordx4 v160, v[78:81], s[98:99] sc1
	v_fmamk_f32 v228, v166, 0x3a000000, v155
	v_mul_f32_e32 v229, 0x4b800000, v228
	v_cmp_gt_f32_e32 vcc, s51, v228
	v_add_u32_e32 v156, 0x80, v146
	s_nop 0
	v_cndmask_b32_e32 v228, v228, v229, vcc
	v_mad_u32_u24 v157, v156, s52, v134
	v_rsq_f32_e32 v228, v228
	s_nop 0
	v_mul_f32_e32 v229, 0x45800000, v228
	s_nop 0
	v_cndmask_b32_e32 v228, v228, v229, vcc
	v_pk_mul_f32 v[62:63], v[62:63], v[228:229] op_sel_hi:[1,0]
	v_pk_mul_f32 v[64:65], v[64:65], v[228:229] op_sel_hi:[1,0]
	v_pk_mul_f32 v[58:59], v[58:59], v[228:229] op_sel_hi:[1,0]
	v_pk_mul_f32 v[60:61], v[60:61], v[228:229] op_sel_hi:[1,0]
	v_pk_mul_f32 v[54:55], v[54:55], v[228:229] op_sel_hi:[1,0]
	v_pk_mul_f32 v[56:57], v[56:57], v[228:229] op_sel_hi:[1,0]
	v_pk_mul_f32 v[50:51], v[50:51], v[228:229] op_sel_hi:[1,0]
	v_pk_mul_f32 v[52:53], v[52:53], v[228:229] op_sel_hi:[1,0]
	v_pk_mul_f32 v[220:221], v[62:63], s[36:37]
	v_pk_mul_f32 v[222:223], v[64:65], s[36:37]
	v_pk_mul_f32 v[224:225], v[58:59], s[36:37]
	v_pk_mul_f32 v[226:227], v[60:61], s[36:37]
	v_exp_f32_e32 v220, v220
	v_exp_f32_e32 v221, v221
	v_exp_f32_e32 v222, v222
	v_exp_f32_e32 v223, v223
	v_exp_f32_e32 v224, v224
	v_exp_f32_e32 v225, v225
	v_exp_f32_e32 v226, v226
	v_exp_f32_e32 v227, v227
	v_pk_add_f32 v[220:221], v[220:221], s[38:39]
	v_pk_add_f32 v[222:223], v[222:223], s[38:39]
	v_pk_add_f32 v[224:225], v[224:225], s[38:39]
	v_pk_add_f32 v[226:227], v[226:227], s[38:39]
	v_rcp_f32_e32 v220, v220
	v_rcp_f32_e32 v221, v221
	v_rcp_f32_e32 v222, v222
	v_rcp_f32_e32 v223, v223
	v_rcp_f32_e32 v224, v224
	v_rcp_f32_e32 v225, v225
	v_rcp_f32_e32 v226, v226
	v_rcp_f32_e32 v227, v227
	v_pk_mul_f32 v[62:63], v[62:63], v[220:221]
; __device__ __forceinline__ float fast_sigmoid(float x) { return __builtin_amdgcn_rcpf(1.0f + __builtin_amdgcn_exp2f(-1.4426950408889634f * x)); }
; __device__ __forceinline__ u32x4 pack8(const f32x4 a, const f32x4 b) { u32x4 w; w.x = cvt_pk_bf16(a[0], a[1]); w.y = cvt_pk_bf16(a[2], a[3]); w.z = cvt_pk_bf16(b[0], b[1]); w.w = cvt_pk_bf16(b[2], b[3]); return w; }
;     __device__ __forceinline__ void operator()(f32x4 (&acc)[2][2][4][2], const Unit& u, int wr, int wc, int fr, int fq) const {
;     ...
;             for (int ai = 0; ai < 2; ++ai)
; #pragma unroll
;                 for (int m = 0; m < 4; ++m) { const int row = ROWOF(ai, m); const float rs = rsqrtf(rsv[ai * 4 + m] * (1.0f / 2048.0f) + EPS);
;                     f32x4 g0 = acc[ai][0][m][0] * rs, g1 = acc[ai][0][m][1] * rs; const f32x4 u0 = acc[ai][1][m][0] * rs, u1 = acc[ai][1][m][1] * rs;
; #pragma unroll
;                     for (int j = 0; j < 4; ++j) { g0[j] = g0[j] * fast_sigmoid(g0[j]) * u0[j]; g1[j] = g1[j] * fast_sigmoid(g1[j]) * u1[j]; }
;                     *(u32x4*)(P.f_() + (size_t)row * DFF + u.pn * 128 + c8) = pack8(g0, g1); }
	v_pk_mul_f32 v[64:65], v[64:65], v[222:223]
	v_pk_mul_f32 v[58:59], v[58:59], v[224:225]
	v_pk_mul_f32 v[60:61], v[60:61], v[226:227]
	v_pk_mul_f32 v[54:55], v[54:55], v[62:63]
	v_pk_mul_f32 v[56:57], v[56:57], v[64:65]
	v_pk_mul_f32 v[50:51], v[50:51], v[58:59]
	v_pk_mul_f32 v[52:53], v[52:53], v[60:61]
	v_cvt_pk_bf16_f32 v62, v54, v55
	v_cvt_pk_bf16_f32 v63, v56, v57
	v_cvt_pk_bf16_f32 v64, v50, v51
	v_cvt_pk_bf16_f32 v65, v52, v53
	global_store_dwordx4 v157, v[62:65], s[98:99] sc1
	v_fmamk_f32 v228, v149, 0x3a000000, v155
	v_mul_f32_e32 v229, 0x4b800000, v228
	v_cmp_gt_f32_e32 vcc, s51, v228
	v_add_u32_e32 v156, 0x90, v146
	s_nop 0
	v_cndmask_b32_e32 v228, v228, v229, vcc
	v_mad_u32_u24 v160, v156, s52, v134
	v_rsq_f32_e32 v228, v228
	s_nop 0
	v_mul_f32_e32 v229, 0x45800000, v228
	s_nop 0
	v_cndmask_b32_e32 v228, v228, v229, vcc
	v_pk_mul_f32 v[46:47], v[46:47], v[228:229] op_sel_hi:[1,0]
	v_pk_mul_f32 v[48:49], v[48:49], v[228:229] op_sel_hi:[1,0]
	v_pk_mul_f32 v[42:43], v[42:43], v[228:229] op_sel_hi:[1,0]
	v_pk_mul_f32 v[44:45], v[44:45], v[228:229] op_sel_hi:[1,0]
	v_pk_mul_f32 v[38:39], v[38:39], v[228:229] op_sel_hi:[1,0]
	v_pk_mul_f32 v[40:41], v[40:41], v[228:229] op_sel_hi:[1,0]
	v_pk_mul_f32 v[34:35], v[34:35], v[228:229] op_sel_hi:[1,0]
	v_pk_mul_f32 v[36:37], v[36:37], v[228:229] op_sel_hi:[1,0]
	v_pk_mul_f32 v[220:221], v[46:47], s[36:37]
	v_pk_mul_f32 v[222:223], v[48:49], s[36:37]
	v_pk_mul_f32 v[224:225], v[42:43], s[36:37]
	v_pk_mul_f32 v[226:227], v[44:45], s[36:37]
	v_exp_f32_e32 v220, v220
	v_exp_f32_e32 v221, v221
	v_exp_f32_e32 v222, v222
	v_exp_f32_e32 v223, v223
	v_exp_f32_e32 v224, v224
	v_exp_f32_e32 v225, v225
	v_exp_f32_e32 v226, v226
	v_exp_f32_e32 v227, v227
	v_pk_add_f32 v[220:221], v[220:221], s[38:39]
	v_pk_add_f32 v[222:223], v[222:223], s[38:39]
	v_pk_add_f32 v[224:225], v[224:225], s[38:39]
	v_pk_add_f32 v[226:227], v[226:227], s[38:39]
	v_rcp_f32_e32 v220, v220
	v_rcp_f32_e32 v221, v221
	v_rcp_f32_e32 v222, v222
	v_rcp_f32_e32 v223, v223
	v_rcp_f32_e32 v224, v224
	v_rcp_f32_e32 v225, v225
	v_rcp_f32_e32 v226, v226
	v_rcp_f32_e32 v227, v227
	v_pk_mul_f32 v[46:47], v[46:47], v[220:221]
	v_pk_mul_f32 v[48:49], v[48:49], v[222:223]
	v_pk_mul_f32 v[42:43], v[42:43], v[224:225]
	v_pk_mul_f32 v[44:45], v[44:45], v[226:227]
	v_pk_mul_f32 v[38:39], v[38:39], v[46:47]
	v_pk_mul_f32 v[40:41], v[40:41], v[48:49]
	v_pk_mul_f32 v[34:35], v[34:35], v[42:43]
	v_pk_mul_f32 v[36:37], v[36:37], v[44:45]
	v_cvt_pk_bf16_f32 v46, v38, v39
	v_cvt_pk_bf16_f32 v47, v40, v41
	v_cvt_pk_bf16_f32 v48, v34, v35
	v_cvt_pk_bf16_f32 v49, v36, v37
	global_store_dwordx4 v160, v[46:49], s[98:99] sc1
	v_fmamk_f32 v228, v148, 0x3a000000, v155
	v_mul_f32_e32 v229, 0x4b800000, v228
	v_cmp_gt_f32_e32 vcc, s51, v228
	v_add_u32_e32 v156, 0xa0, v146
	s_nop 0
	v_cndmask_b32_e32 v228, v228, v229, vcc
	v_mad_u32_u24 v157, v156, s52, v134
	v_rsq_f32_e32 v228, v228
	s_nop 0
	v_mul_f32_e32 v229, 0x45800000, v228
	s_nop 0
	v_cndmask_b32_e32 v228, v228, v229, vcc
	v_pk_mul_f32 v[30:31], v[30:31], v[228:229] op_sel_hi:[1,0]
	v_pk_mul_f32 v[32:33], v[32:33], v[228:229] op_sel_hi:[1,0]
	v_pk_mul_f32 v[26:27], v[26:27], v[228:229] op_sel_hi:[1,0]
	v_pk_mul_f32 v[28:29], v[28:29], v[228:229] op_sel_hi:[1,0]
	v_pk_mul_f32 v[22:23], v[22:23], v[228:229] op_sel_hi:[1,0]
	v_pk_mul_f32 v[24:25], v[24:25], v[228:229] op_sel_hi:[1,0]
	v_pk_mul_f32 v[18:19], v[18:19], v[228:229] op_sel_hi:[1,0]
	v_pk_mul_f32 v[20:21], v[20:21], v[228:229] op_sel_hi:[1,0]
	v_pk_mul_f32 v[220:221], v[30:31], s[36:37]
	v_pk_mul_f32 v[222:223], v[32:33], s[36:37]
	v_pk_mul_f32 v[224:225], v[26:27], s[36:37]
	v_pk_mul_f32 v[226:227], v[28:29], s[36:37]
	v_exp_f32_e32 v220, v220
	v_exp_f32_e32 v221, v221
	v_exp_f32_e32 v222, v222
	v_exp_f32_e32 v223, v223
	v_exp_f32_e32 v224, v224
	v_exp_f32_e32 v225, v225
	v_exp_f32_e32 v226, v226
	v_exp_f32_e32 v227, v227
	v_pk_add_f32 v[220:221], v[220:221], s[38:39]
	v_pk_add_f32 v[222:223], v[222:223], s[38:39]
	v_pk_add_f32 v[224:225], v[224:225], s[38:39]
	v_pk_add_f32 v[226:227], v[226:227], s[38:39]
	v_rcp_f32_e32 v220, v220
	v_rcp_f32_e32 v221, v221
	v_rcp_f32_e32 v222, v222
	v_rcp_f32_e32 v223, v223
	v_rcp_f32_e32 v224, v224
	v_rcp_f32_e32 v225, v225
	v_rcp_f32_e32 v226, v226
	v_rcp_f32_e32 v227, v227
	v_pk_mul_f32 v[30:31], v[30:31], v[220:221]
	v_pk_mul_f32 v[32:33], v[32:33], v[222:223]
	v_pk_mul_f32 v[26:27], v[26:27], v[224:225]
	v_pk_mul_f32 v[28:29], v[28:29], v[226:227]
	v_pk_mul_f32 v[22:23], v[22:23], v[30:31]
	v_pk_mul_f32 v[24:25], v[24:25], v[32:33]
	v_pk_mul_f32 v[18:19], v[18:19], v[26:27]
	v_pk_mul_f32 v[20:21], v[20:21], v[28:29]
	v_cvt_pk_bf16_f32 v30, v22, v23
	v_cvt_pk_bf16_f32 v31, v24, v25
	v_cvt_pk_bf16_f32 v32, v18, v19
	v_cvt_pk_bf16_f32 v33, v20, v21
	global_store_dwordx4 v157, v[30:33], s[98:99] sc1
	v_fmamk_f32 v228, v147, 0x3a000000, v155
	v_mul_f32_e32 v229, 0x4b800000, v228
	v_cmp_gt_f32_e32 vcc, s51, v228
	v_add_u32_e32 v156, 0xb0, v146
	s_nop 0
	v_cndmask_b32_e32 v228, v228, v229, vcc
	v_mad_u32_u24 v160, v156, s52, v134
	v_rsq_f32_e32 v228, v228
	s_nop 0
	v_mul_f32_e32 v229, 0x45800000, v228
	s_nop 0
	v_cndmask_b32_e32 v228, v228, v229, vcc
	v_pk_mul_f32 v[14:15], v[14:15], v[228:229] op_sel_hi:[1,0]
	v_pk_mul_f32 v[16:17], v[16:17], v[228:229] op_sel_hi:[1,0]
	v_pk_mul_f32 v[10:11], v[10:11], v[228:229] op_sel_hi:[1,0]
	v_pk_mul_f32 v[12:13], v[12:13], v[228:229] op_sel_hi:[1,0]
	v_pk_mul_f32 v[6:7], v[6:7], v[228:229] op_sel_hi:[1,0]
	v_pk_mul_f32 v[8:9], v[8:9], v[228:229] op_sel_hi:[1,0]
	v_pk_mul_f32 v[2:3], v[2:3], v[228:229] op_sel_hi:[1,0]
	v_pk_mul_f32 v[4:5], v[4:5], v[228:229] op_sel_hi:[1,0]
	v_pk_mul_f32 v[220:221], v[14:15], s[36:37]
	v_pk_mul_f32 v[222:223], v[16:17], s[36:37]
	v_pk_mul_f32 v[224:225], v[10:11], s[36:37]
	v_pk_mul_f32 v[226:227], v[12:13], s[36:37]
	v_exp_f32_e32 v220, v220
	v_exp_f32_e32 v221, v221
	v_exp_f32_e32 v222, v222
	v_exp_f32_e32 v223, v223
	v_exp_f32_e32 v224, v224
	v_exp_f32_e32 v225, v225
	v_exp_f32_e32 v226, v226
	v_exp_f32_e32 v227, v227
	v_pk_add_f32 v[220:221], v[220:221], s[38:39]
	v_pk_add_f32 v[222:223], v[222:223], s[38:39]
	v_pk_add_f32 v[224:225], v[224:225], s[38:39]
	v_pk_add_f32 v[226:227], v[226:227], s[38:39]
	v_rcp_f32_e32 v220, v220
	v_rcp_f32_e32 v221, v221
	v_rcp_f32_e32 v222, v222
	v_rcp_f32_e32 v223, v223
	v_rcp_f32_e32 v224, v224
	v_rcp_f32_e32 v225, v225
	v_rcp_f32_e32 v226, v226
	v_rcp_f32_e32 v227, v227
	v_pk_mul_f32 v[14:15], v[14:15], v[220:221]
	v_pk_mul_f32 v[16:17], v[16:17], v[222:223]
	v_pk_mul_f32 v[10:11], v[10:11], v[224:225]
	v_pk_mul_f32 v[12:13], v[12:13], v[226:227]
	v_pk_mul_f32 v[6:7], v[6:7], v[14:15]
	v_pk_mul_f32 v[8:9], v[8:9], v[16:17]
	v_pk_mul_f32 v[2:3], v[2:3], v[10:11]
	v_pk_mul_f32 v[4:5], v[4:5], v[12:13]
	v_cvt_pk_bf16_f32 v14, v6, v7
	v_cvt_pk_bf16_f32 v15, v8, v9
	v_cvt_pk_bf16_f32 v16, v2, v3
	v_cvt_pk_bf16_f32 v17, v4, v5
	s_andn2_b64 vcc, exec, s[18:19]
	s_mov_b64 s[18:19], -1
	global_store_dwordx4 v160, v[14:17], s[98:99] sc1
	s_cbranch_vccnz .LBB0_995
; #define PG8_BAR __builtin_amdgcn_s_barrier()
; template <class Sched, class Epi>
; __device__ __forceinline__ void gemm_run(LAS unsigned char* lds, const Sched& S, const Epi& E) {
;     ...
;         }
;         if (wr == 0) PG8_BAR;
;         if constexpr (!Epi::AFTER_DRAIN) E(acc, cur, wr, wc, fr, fq);
;         if (!has_next) break;
; #pragma unroll
;         for (int a = 0; a < 2; ++a)
; #pragma unroll
;             for (int b = 0; b < 2; ++b)
; #pragma unroll
;                 for (int m = 0; m < 4; ++m)
; #pragma unroll
;                     for (int n = 0; n < 2; ++n) acc[a][b][m][n] = (f32x4){0.f, 0.f, 0.f, 0.f};
;         cur = nxt; cA = nA; cB = nB; lda = nlda; ldb = nldb; ++ui;
;         if (wr == 1) PG8_BAR;
;     }
	s_andn2_b64 vcc, exec, s[4:5]
	s_cbranch_vccnz .LBB0_994
	s_barrier
	s_branch .LBB0_994
